# window-attention tile loop: fully valid interior tiles take the existing mask-free path (wave-uniform test)
# speedup vs baseline: 1.0058x; 1.0040x over previous
; DI int ltid() { int t = threadIdx.x & 255; asm volatile("" : "+v"(t)); return t; }
; template <int MODE>
; DI void attn64_wave(const Params& p, int layer, int b, int hq, int qrow0, int t0, const float* rpb_lds, unsigned char* wlds) {
;   constexpr bool isC = (MODE == 0 || MODE == 2);
;   const int lane = ltid() & 63, qi = lane & 31, hh = lane >> 5;
;   const int pr = (qi & 19) | ((qi & 4) << 1) | ((qi & 8) >> 1);
;   const float* gqp = (isC ? p.na_q_gain : p.sw_q_gain) + layer * 64;
;   const float* gkp = (isC ? p.na_k_gain : p.sw_k_gain) + layer * 64;
;   const float gq = wave_max(fabsf(gqp[lane])), gk = wave_max(fabsf(gkp[lane]));
;   const float negM2 = -(0.125f * LOG2E * 64.f * 1.02f) * gq * gk;
;   const int kvh = isC ? hq : (hq >> 1);
;   const int qcol = isC ? 2048 + 64 * hq : 2816 + 64 * hq;
;   const int kcol = isC ? 2304 + 64 * hq : 3072 + 64 * kvh;
;   const bf16_t* vt = isC ? p.VtC + (size_t)(b * 4 + hq) * 64 * UA : p.VtD + (size_t)(b * 2 + kvh) * 64 * UA;
;   const bf16_t* qp = p.P + (size_t)(qrow0 + qi) * NP + qcol + 8 * hh;
;   bf16x8 qf[4];
; #pragma unroll
;   for (int ks = 0; ks < 4; ++ks) qf[ks] = *(const bf16x8*)(qp + ks * 16);
;   f32x16 o[2];
; #pragma unroll
;   for (int dh = 0; dh < 2; ++dh)
; #pragma unroll
;     for (int i = 0; i < 16; ++i) o[dh][i] = 0.f;
;   float ls = 0.f;
;   constexpr int NT = MODE == 0 ? 24 : (MODE == 1 ? 18 : 8);
;   const int r = t0 >> 6, c = (t0 & 63) + qi;
;   const int rs = min(max(r - 4, 0), 248), ws = min(max(c - 8, 0), 48);
.LBB0_419:
	s_nop 2
	v_mov_b32_e32 v10, v212
	v_readlane_b32 s2, v255, 4
	v_and_b32_e32 v4, 63, v10
	v_lshlrev_b32_e32 v0, 2, v4
	v_readlane_b32 s3, v255, 5
	v_readlane_b32 s24, v255, 6
	v_readlane_b32 s25, v255, 7
	v_cmp_lt_i32_e32 vcc, v218, v217
	v_lshlrev_b32_e32 v23, 4, v4
	v_mov_b32_e32 v5, v193
	global_load_dword v11, v0, s[2:3]
	v_cndmask_b32_e32 v2, v216, v218, vcc
	global_load_dword v12, v0, s[24:25]
	s_and_b32 s2, s38, 0x3f80
	s_sub_i32 s3, s40, s27
	v_add_u32_e32 v132, s2, v152
	s_lshr_b32 s2, s3, 7
	s_ashr_i32 s27, s3, 9
	v_cmp_lt_i32_e32 vcc, v219, v217
	s_bfe_u32 s26, s3, 0x20007
	s_lshl_b32 s3, s3, 7
	s_bfe_u32 s29, s2, 0x10001
	s_lshl_b32 s2, s27, 1
	v_cndmask_b32_e32 v6, v216, v219, vcc
	v_cmp_lt_i32_e32 vcc, v220, v217
	s_and_b32 s3, s3, 0x3f80
	s_lshl_b32 s22, s26, 6
	s_or_b32 s2, s29, s2
	v_cndmask_b32_e32 v8, v216, v220, vcc
	s_lshl_b32 s28, s27, 14
	v_add_u32_e32 v20, s3, v152
	s_mov_b64 s[44:45], s[22:23]
	s_lshl_b32 s22, s26, 7
	s_mul_hi_i32 s3, s2, 0x208000
	s_mul_i32 s2, s2, 0x208000
	v_cmp_lt_i32_e32 vcc, v221, v217
	v_lshlrev_b32_e32 v133, 2, v2
	v_lshlrev_b32_e32 v16, 2, v8
	v_lshlrev_b32_e32 v2, 1, v10
	v_lshlrev_b32_e32 v8, 4, v10
	s_add_u32 s2, s86, s2
	v_cndmask_b32_e32 v9, v216, v221, vcc
	v_and_b32_e32 v18, 31, v10
	v_and_b32_e32 v21, 8, v2
	v_and_b32_e32 v2, 0x70, v8
	v_add_u32_e32 v8, s28, v20
	v_and_b32_e32 v4, 48, v23
	s_addc_u32 s3, s87, s3
	v_mov_b64_e32 v[0:1], s[78:79]
	v_lshlrev_b32_e32 v17, 2, v9
	v_or_b32_e32 v144, v18, v8
	v_lshl_add_u64 v[8:9], s[2:3], 0, v[4:5]
	v_bfe_u32 v155, v10, 5, 1
	v_mad_i64_i32 v[0:1], s[24:25], v144, s20, v[0:1]
	v_cmp_lt_i32_e32 vcc, v222, v217
	v_lshlrev_b32_e32 v15, 2, v6
	v_lshrrev_b32_e32 v6, 1, v10
	v_bfe_u32 v19, v10, 2, 4
	v_lshlrev_b32_e32 v192, 4, v155
	v_lshl_add_u64 v[0:1], v[0:1], 0, s[22:23]
	v_cndmask_b32_e32 v13, v216, v222, vcc
	v_cmp_lt_i32_e32 vcc, v223, v217
	v_mov_b32_e32 v7, v193
	v_and_b32_e32 v22, 4, v6
	v_mul_u32_u24_e32 v6, 0x8200, v19
	v_lshl_add_u64 v[0:1], v[0:1], 0, v[192:193]
	s_mov_b64 s[2:3], 0x1600
	v_cndmask_b32_e32 v14, v216, v223, vcc
	v_lshl_add_u64 v[128:129], v[8:9], 0, v[6:7]
	v_lshl_add_u64 v[6:7], v[0:1], 0, s[2:3]
	v_add_co_u32_e32 v0, vcc, s63, v0
	global_load_dwordx4 v[80:83], v[128:129], off
	s_nop 0
	v_addc_co_u32_e32 v1, vcc, 0, v1, vcc
	global_load_dwordx4 v[64:67], v[6:7], off offset:32
	global_load_dwordx4 v[68:71], v[6:7], off offset:64
	global_load_dwordx4 v[72:75], v[0:1], off offset:1536
	global_load_dwordx4 v[76:79], v[6:7], off offset:96
	s_lshl_b32 s24, s29, 7
	s_add_u32 s24, s78, s24
	v_mov_b32_e32 v3, v193
	s_addc_u32 s25, s79, 0
	v_lshl_add_u64 v[2:3], s[24:25], 0, v[2:3]
	s_mov_b64 s[2:3], 0x1800
	v_lshl_add_u64 v[130:131], v[2:3], 0, s[2:3]
	v_lshlrev_b32_e32 v13, 2, v13
	s_lshl_b32 s22, s27, 8
	v_bfe_u32 v134, v10, 3, 3
	s_add_i32 s22, s22, 0x8000
	v_lshlrev_b32_e32 v14, 2, v14
	v_mov_b32_e32 v135, 0
	s_waitcnt vmcnt(6)
	v_and_b32_e32 v5, 0x7fffffff, v11
	ds_bpermute_b32 v5, v133, v5
	v_max_f32_e64 v0, |v11|, |v11|
	s_waitcnt vmcnt(5)
	v_and_b32_e32 v2, 0x7fffffff, v12
	ds_bpermute_b32 v2, v133, v2
	v_max_f32_e64 v3, |v12|, |v12|
	s_waitcnt lgkmcnt(1)
	v_max_f32_e32 v1, v5, v5
	v_max_f32_e32 v0, v0, v1
	ds_bpermute_b32 v1, v15, v0
	s_waitcnt lgkmcnt(1)
	v_max_f32_e32 v2, v2, v2
	v_max_f32_e32 v2, v3, v2
	ds_bpermute_b32 v3, v15, v2
	v_or_b32_e32 v5, s22, v134
	s_waitcnt lgkmcnt(1)
	v_max_f32_e32 v1, v1, v1
	v_max_f32_e32 v0, v0, v1
	ds_bpermute_b32 v1, v16, v0
	s_waitcnt lgkmcnt(1)
; template <int MODE>
; DI void attn64_wave(const Params& p, int layer, int b, int hq, int qrow0, int t0, const float* rpb_lds, unsigned char* wlds) {
;     ...
;   const float gq = wave_max(fabsf(gqp[lane])), gk = wave_max(fabsf(gkp[lane]));
;   const float negM2 = -(0.125f * LOG2E * 64.f * 1.02f) * gq * gk;
;   const int kvh = isC ? hq : (hq >> 1);
;   const int qcol = isC ? 2048 + 64 * hq : 2816 + 64 * hq;
;   const int kcol = isC ? 2304 + 64 * hq : 3072 + 64 * kvh;
;   const bf16_t* vt = isC ? p.VtC + (size_t)(b * 4 + hq) * 64 * UA : p.VtD + (size_t)(b * 2 + kvh) * 64 * UA;
;   const bf16_t* qp = p.P + (size_t)(qrow0 + qi) * NP + qcol + 8 * hh;
;   bf16x8 qf[4];
; #pragma unroll
;   for (int ks = 0; ks < 4; ++ks) qf[ks] = *(const bf16x8*)(qp + ks * 16);
;   f32x16 o[2];
; #pragma unroll
;   for (int dh = 0; dh < 2; ++dh)
; #pragma unroll
;     for (int i = 0; i < 16; ++i) o[dh][i] = 0.f;
;   float ls = 0.f;
;   constexpr int NT = MODE == 0 ? 24 : (MODE == 1 ? 18 : 8);
;   const int r = t0 >> 6, c = (t0 & 63) + qi;
;   const int rs = min(max(r - 4, 0), 248), ws = min(max(c - 8, 0), 48);
	v_max_f32_e32 v3, v3, v3
	v_max_f32_e32 v2, v2, v3
	ds_bpermute_b32 v3, v16, v2
	v_or_b32_e32 v8, 8, v5
	s_waitcnt lgkmcnt(1)
	v_max_f32_e32 v1, v1, v1
	v_max_f32_e32 v6, v0, v1
	ds_bpermute_b32 v7, v17, v6
	s_waitcnt lgkmcnt(1)
	v_max_f32_e32 v3, v3, v3
	v_mad_u64_u32 v[0:1], s[2:3], v5, s20, v[130:131]
	v_max_f32_e32 v9, v2, v3
	s_waitcnt lgkmcnt(0)
	v_max_f32_e32 v7, v7, v7
	v_max_f32_e32 v6, v6, v7
	ds_bpermute_b32 v7, v13, v6
	ds_bpermute_b32 v11, v17, v9
	s_mov_b32 s29, 0
	s_mov_b32 s27, 32
	v_ashrrev_i32_e32 v145, 31, v144
	s_waitcnt lgkmcnt(1)
	v_max_f32_e32 v2, v7, v7
	v_max_f32_e32 v6, v6, v2
	v_mad_u64_u32 v[2:3], s[2:3], v8, s20, v[130:131]
	global_load_dwordx4 v[84:87], v[0:1], off
	global_load_dwordx4 v[88:91], v[2:3], off
	v_add_co_u32_e32 v0, vcc, s61, v128
	v_lshlrev_b32_e32 v3, 3, v155
	s_nop 0
	v_addc_co_u32_e32 v1, vcc, 0, v129, vcc
	global_load_dwordx4 v[92:95], v[0:1], off
	v_or_b32_e32 v0, 16, v5
	v_mad_u64_u32 v[0:1], s[2:3], v0, s20, v[130:131]
	global_load_dwordx4 v[96:99], v[0:1], off
	v_add_co_u32_e32 v0, vcc, s62, v128
	s_addk_i32 s28, 0xff00
	s_nop 0
	v_addc_co_u32_e32 v1, vcc, 0, v129, vcc
	global_load_dwordx4 v[100:103], v[0:1], off
	v_or_b32_e32 v0, 24, v5
	v_mad_u64_u32 v[0:1], s[2:3], v0, s20, v[130:131]
	global_load_dwordx4 v[104:107], v[0:1], off
	v_add_co_u32_e32 v0, vcc, 0x186000, v128
	v_and_b32_e32 v5, 19, v10
	s_nop 0
	v_addc_co_u32_e32 v1, vcc, 0, v129, vcc
	global_load_dwordx4 v[108:111], v[0:1], off
	s_waitcnt lgkmcnt(0)
	v_max_f32_e32 v1, v11, v11
	v_max_f32_e32 v1, v9, v1
	ds_bpermute_b32 v2, v13, v1
	ds_bpermute_b32 v0, v14, v6
	v_add_u32_e32 v136, 0xfffffe80, v20
	v_sub_u32_e32 v137, v3, v18
	v_mov_b32_e32 v3, v135
	s_waitcnt lgkmcnt(1)
	v_max_f32_e32 v2, v2, v2
	v_max_f32_e32 v1, v1, v2
	ds_bpermute_b32 v2, v14, v1
	s_waitcnt lgkmcnt(1)
	v_max_f32_e32 v0, v0, v0
	v_max_f32_e32 v0, v6, v0
	v_mul_f32_e32 v0, 0xc13c5bb7, v0
	v_mad_u32_u24 v6, v18, s60, v153
	s_waitcnt lgkmcnt(0)
	v_max_f32_e32 v2, v2, v2
	v_max_f32_e32 v1, v1, v2
	v_or3_b32 v2, v5, v21, v22
	v_mul_f32_e32 v32, v0, v1
	v_mad_u32_u24 v0, v134, s59, v153
	v_and_b32_e32 v1, 0x70, v23
	v_mad_u32_u24 v5, v19, s60, v153
	v_mad_u32_u24 v2, v2, s59, v153
	v_mov_b32_e32 v33, v32
	v_mov_b32_e32 v34, v32
	v_mov_b32_e32 v35, v32
	v_mov_b32_e32 v36, v32
	v_mov_b32_e32 v37, v32
	v_mov_b32_e32 v38, v32
	v_mov_b32_e32 v39, v32
	v_mov_b32_e32 v40, v32
	v_mov_b32_e32 v41, v32
	v_mov_b32_e32 v42, v32
	v_mov_b32_e32 v43, v32
	v_mov_b32_e32 v44, v32
	v_mov_b32_e32 v45, v32
	v_mov_b32_e32 v46, v32
	v_mov_b32_e32 v47, v32
	v_add_u32_e32 v138, v0, v1
	v_add_u32_e32 v139, v5, v4
	v_add_u32_e32 v140, v2, v192
	v_add_u32_e32 v141, v6, v192
	v_mov_b32_e32 v0, 0
	v_mov_b32_e32 v1, v135
	v_mov_b32_e32 v2, v135
	v_mov_b32_e32 v4, v135
	v_mov_b32_e32 v5, v135
	v_mov_b32_e32 v6, v135
	v_mov_b32_e32 v7, v135
	v_mov_b32_e32 v8, v135
	v_mov_b32_e32 v9, v135
	v_mov_b32_e32 v10, v135
	v_mov_b32_e32 v11, v135
	v_mov_b32_e32 v12, v135
	v_mov_b32_e32 v13, v135
	v_mov_b32_e32 v14, v135
	v_mov_b32_e32 v15, v135
	v_mov_b32_e32 v16, 0
	v_mov_b32_e32 v17, v135
	v_mov_b32_e32 v18, v135
	v_mov_b32_e32 v19, v135
	v_mov_b32_e32 v20, v135
	v_mov_b32_e32 v21, v135
	v_mov_b32_e32 v22, v135
	v_mov_b32_e32 v23, v135
	v_mov_b32_e32 v24, v135
	v_mov_b32_e32 v25, v135
	v_mov_b32_e32 v26, v135
	v_mov_b32_e32 v27, v135
	v_mov_b32_e32 v28, v135
	v_mov_b32_e32 v29, v135
	v_mov_b32_e32 v30, v135
	v_mov_b32_e32 v31, v135
	v_readfirstlane_b32 s98, v132
	s_add_i32 s98, s98, 0xffffff80
	s_cmp_lt_u32 s98, 0x3ee1
	s_cselect_b64 s[98:99], -1, 0
	s_branch .LBB0_421

; template <int MODE>
; DI void attn64_wave(const Params& p, int layer, int b, int hq, int qrow0, int t0, const float* rpb_lds, unsigned char* wlds) {
;     ...
;   auto tile_u = [&](int t) -> int {
;     if (t < 8) return 32 * t;
;     if (MODE == 0) return CTX + (rs + ((t - 8) >> 1)) * 64 + ((t - 8) & 1) * 32;
;     const int kt0 = t0 - 128 + 32 * (t - 8);
;     return CTX + min(max(kt0, 0), SEQ - 32);
;   };
;   auto load_tile = [&](Frag64& f, int t) { frag64_load(f, p.P, vt, b, tile_u(t), kcol, lane); };
;   unsigned char* Kw = wlds; unsigned char* Vw = wlds + W64_KB;
;   auto compute_tile = [&](const Frag64& f, int t) {
; #pragma unroll
;     for (int i = 0; i < 4; ++i) {
;       *(u32x4*)(Kw + ((lane >> 3) + 8 * i) * LDS_STRIDE + (lane & 7) * 16) = f.k[i];
;       *(u32x4*)(Vw + ((lane >> 2) + 16 * i) * W64_VSTR + (lane & 3) * 16) = f.v[i];
;     }
;     bf16x8 kf[4], vf[2][2];
; #pragma unroll
;     for (int ks = 0; ks < 4; ++ks) kf[ks] = __builtin_bit_cast(bf16x8, *(const u32x4*)(Kw + pr * LDS_STRIDE + (16 * ks + 8 * hh) * 2));
; #pragma unroll
;     for (int dh = 0; dh < 2; ++dh)
; #pragma unroll
;       for (int s2 = 0; s2 < 2; ++s2) vf[dh][s2] = __builtin_bit_cast(bf16x8, *(const u32x4*)(Vw + (32 * dh + qi) * W64_VSTR + (16 * s2 + 8 * hh) * 2));
;     f32x16 s;
; #pragma unroll
;     for (int i = 0; i < 16; ++i) s[i] = negM2;
; #pragma unroll
;     for (int ks = 0; ks < 4; ++ks) s = MFMA32(kf[ks], qf[ks], s);
;     float pe[16];
;     if (t < 8) {
; #pragma unroll
;       for (int i = 0; i < 16; ++i) pe[i] = fexp2(s[i]);
;     } else if (MODE == 0) {
;       const int kr = rs + ((t - 8) >> 1), hf = (t - 8) & 1;
;       const float* rrow = rpb + (kr - r + 7) * 31 + 15 - c;
; #pragma unroll
;       for (int i = 0; i < 16; ++i) {
;         const int kc = hf * 32 + 16 * (i >> 3) + 8 * hh + (i & 7);
;         const bool valid = (kc >= ws) && (kc < ws + 16);
;         const int kcc = min(max(kc, ws), ws + 15);
;         pe[i] = fexp2(valid ? s[i] + rrow[kcc] : -1e30f);
;       }
;     } else {
;       const int jt = t - 8, kt0 = t0 - 128 + 32 * jt;
;       const bool tile_ok = (jt < 9) && (kt0 >= 0) && (kt0 < SEQ);
; #pragma unroll
;       for (int i = 0; i < 16; ++i) {
;         const int dd = kt0 + 16 * (i >> 3) + 8 * hh + (i & 7) - qt;
;         pe[i] = fexp2((tile_ok && dd <= 128 && dd >= -128) ? s[i] : -1e30f);
.LBB0_421:
	v_add_u32_e32 v146, s27, v132
	s_cmp_gt_u32 s29, 7
	v_add_u32_e32 v142, 0xfffffe80, v146
	s_cselect_b64 s[24:25], -1, 0
	s_cmp_lt_u32 s29, 8
	v_med3_i32 v48, v142, 0, v236
	v_add_u32_e32 v48, 0x100, v48
	v_mov_b32_e32 v49, s27
	s_cselect_b64 vcc, -1, 0
	v_cndmask_b32_e32 v192, v48, v49, vcc
	v_add_u32_e32 v126, v192, v134
	s_movk_i32 s2, 0x100
	v_mov_b32_e32 v127, s28
	v_mov_b32_e32 v143, s22
	v_cmp_gt_u32_e32 vcc, s2, v126
	v_lshl_add_u64 v[124:125], v[192:193], 1, v[128:129]
	global_load_dwordx4 v[116:119], v[124:125], off
	v_cndmask_b32_e32 v48, v127, v143, vcc
	v_add_u32_e32 v48, v48, v126
	v_mad_i64_i32 v[48:49], s[2:3], v48, s20, v[130:131]
	s_movk_i32 s2, 0xf8
	s_nop 0
	v_cmp_gt_u32_e32 vcc, s2, v126
	global_load_dwordx4 v[112:115], v[48:49], off
	s_nop 0
	v_cndmask_b32_e32 v48, v127, v143, vcc
	v_add3_u32 v48, v126, v48, 8
	v_mad_i64_i32 v[48:49], s[2:3], v48, s20, v[130:131]
	global_load_dwordx4 v[120:123], v[48:49], off
	s_waitcnt vmcnt(9)
	ds_write_b128 v138, v[84:87] offset:8192
	s_waitcnt vmcnt(8)
	ds_write_b128 v139, v[80:83] offset:12800
	s_waitcnt vmcnt(8)
	ds_write_b128 v138, v[88:91] offset:9344
	s_waitcnt vmcnt(7)
	ds_write_b128 v139, v[92:95] offset:14080
	s_waitcnt vmcnt(6)
	ds_write_b128 v138, v[96:99] offset:10496
	s_waitcnt vmcnt(5)
	ds_write_b128 v139, v[100:103] offset:15360
	s_waitcnt vmcnt(4)
	ds_write_b128 v138, v[104:107] offset:11648
	s_waitcnt vmcnt(3)
	ds_write_b128 v139, v[108:111] offset:16640
	ds_read_b128 v[80:83], v140 offset:8192
	ds_read_b128 v[84:87], v140 offset:8224
	v_add_co_u32_e32 v48, vcc, s61, v124
	s_movk_i32 s2, 0xf0
	s_nop 0
	v_addc_co_u32_e32 v49, vcc, 0, v125, vcc
	v_cmp_gt_u32_e32 vcc, s2, v126
	global_load_dwordx4 v[92:95], v[48:49], off
	ds_read_b128 v[148:151], v140 offset:8288
	v_cndmask_b32_e32 v48, v127, v143, vcc
	v_add3_u32 v48, v126, v48, 16
	v_mad_i64_i32 v[48:49], s[2:3], v48, s20, v[130:131]
	global_load_dwordx4 v[96:99], v[48:49], off
	s_waitcnt lgkmcnt(2)
	v_mfma_f32_32x32x16_bf16 v[48:63], v[80:83], v[72:75], v[32:47]
	v_add_co_u32_e32 v80, vcc, s62, v124
	s_movk_i32 s2, 0xe8
	s_nop 0
	v_addc_co_u32_e32 v81, vcc, 0, v125, vcc
	v_cmp_gt_u32_e32 vcc, s2, v126
	global_load_dwordx4 v[100:103], v[80:81], off
	s_waitcnt lgkmcnt(1)
	v_mfma_f32_32x32x16_bf16 v[48:63], v[84:87], v[64:67], v[48:63]
	v_cndmask_b32_e32 v80, v127, v143, vcc
	v_add3_u32 v88, v126, v80, 24
	v_mad_i64_i32 v[84:85], s[2:3], v88, s20, v[130:131]
	global_load_dwordx4 v[104:107], v[84:85], off
	v_add_co_u32_e32 v84, vcc, s64, v124
	ds_read_b128 v[80:83], v140 offset:8256
	s_nop 0
	v_addc_co_u32_e32 v85, vcc, 0, v125, vcc
	global_load_dwordx4 v[108:111], v[84:85], off
	s_waitcnt lgkmcnt(0)
	v_mfma_f32_32x32x16_bf16 v[48:63], v[80:83], v[68:71], v[48:63]
	ds_read_b128 v[124:127], v141 offset:12800
	ds_read_b128 v[84:87], v141 offset:12832
	ds_read_b128 v[88:91], v141 offset:15360
	ds_read_b128 v[80:83], v141 offset:15392
	s_sub_u32 s100, s29, 10
	s_cmp_lt_u32 s100, 5
	s_cselect_b64 s[100:101], s[98:99], 0
	s_andn2_b64 s[100:101], s[24:25], s[100:101]
	s_and_b64 vcc, exec, s[100:101]
	v_add_u32_e32 v143, s27, v137
	v_mfma_f32_32x32x16_bf16 v[48:63], v[148:151], v[76:79], v[48:63]
	s_cbranch_vccz .LBB0_423
	v_add_u32_e32 v146, 0xfffffe60, v146
	s_movk_i32 s2, 0x4000
	v_cmp_gt_u32_e32 vcc, s2, v146
	v_add_u32_e32 v146, 0xfffffee0, v143
	s_movk_i32 s30, 0x101
	v_cmp_gt_u32_e64 s[2:3], s30, v146
	s_and_b64 s[2:3], vcc, s[2:3]
	v_add_u32_e32 v147, 0xfffffee1, v143
	s_nop 2
	v_cndmask_b32_e64 v146, v237, v48, s[2:3]
	v_cmp_gt_u32_e64 s[2:3], s30, v147
	s_and_b64 s[2:3], vcc, s[2:3]
	v_add_u32_e32 v148, 0xfffffee2, v143
	v_cndmask_b32_e64 v147, v237, v49, s[2:3]
	v_cmp_gt_u32_e64 s[2:3], s30, v148
	s_and_b64 s[2:3], vcc, s[2:3]
	v_add_u32_e32 v149, 0xfffffee3, v143
	v_cndmask_b32_e64 v148, v237, v50, s[2:3]
	v_cmp_gt_u32_e64 s[2:3], s30, v149
	s_and_b64 s[2:3], vcc, s[2:3]
	v_add_u32_e32 v150, 0xfffffee4, v143
	v_cndmask_b32_e64 v149, v237, v51, s[2:3]
	v_cmp_gt_u32_e64 s[2:3], s30, v150
	s_and_b64 s[2:3], vcc, s[2:3]
	v_add_u32_e32 v151, 0xfffffee5, v143
	v_cndmask_b32_e64 v150, v237, v52, s[2:3]
	v_cmp_gt_u32_e64 s[2:3], s30, v151
	s_and_b64 s[2:3], vcc, s[2:3]
	v_add_u32_e32 v156, 0xfffffee6, v143
	v_cndmask_b32_e64 v151, v237, v53, s[2:3]
	v_cmp_gt_u32_e64 s[2:3], s30, v156
	s_and_b64 s[2:3], vcc, s[2:3]
	v_add_u32_e32 v157, 0xfffffee7, v143
	v_cndmask_b32_e64 v156, v237, v54, s[2:3]
	v_cmp_gt_u32_e64 s[2:3], s30, v157
	s_and_b64 s[2:3], vcc, s[2:3]
	v_add_u32_e32 v158, 0xfffffef0, v143
	v_cndmask_b32_e64 v157, v237, v55, s[2:3]
	v_cmp_gt_u32_e64 s[2:3], s30, v158
	s_and_b64 s[2:3], vcc, s[2:3]
	v_add_u32_e32 v159, 0xfffffef1, v143
	v_cndmask_b32_e64 v158, v237, v56, s[2:3]
	v_cmp_gt_u32_e64 s[2:3], s30, v159
	s_and_b64 s[2:3], vcc, s[2:3]
	v_add_u32_e32 v160, 0xfffffef2, v143
	v_cndmask_b32_e64 v159, v237, v57, s[2:3]
	v_cmp_gt_u32_e64 s[2:3], s30, v160
	s_and_b64 s[2:3], vcc, s[2:3]
	v_add_u32_e32 v161, 0xfffffef3, v143
	v_cndmask_b32_e64 v160, v237, v58, s[2:3]
	v_cmp_gt_u32_e64 s[2:3], s30, v161
	s_and_b64 s[2:3], vcc, s[2:3]
	v_add_u32_e32 v162, 0xfffffef4, v143
	v_cndmask_b32_e64 v161, v237, v59, s[2:3]
	v_cmp_gt_u32_e64 s[2:3], s30, v162
	s_and_b64 s[2:3], vcc, s[2:3]
	v_add_u32_e32 v163, 0xfffffef5, v143
	v_cndmask_b32_e64 v162, v237, v60, s[2:3]
	v_cmp_gt_u32_e64 s[2:3], s30, v163
	s_and_b64 s[2:3], vcc, s[2:3]
	v_add_u32_e32 v164, 0xfffffef6, v143
	v_cndmask_b32_e64 v163, v237, v61, s[2:3]
	v_cmp_gt_u32_e64 s[2:3], s30, v164
	s_and_b64 s[2:3], vcc, s[2:3]
	v_add_u32_e32 v165, 0xfffffef7, v143
	v_cndmask_b32_e64 v164, v237, v62, s[2:3]
	v_cmp_gt_u32_e64 s[2:3], s30, v165
	s_and_b64 vcc, vcc, s[2:3]
	v_exp_f32_e32 v146, v146
	v_exp_f32_e32 v147, v147
	v_exp_f32_e32 v148, v148
	v_exp_f32_e32 v149, v149
	v_exp_f32_e32 v150, v150
	v_exp_f32_e32 v151, v151
	v_exp_f32_e32 v156, v156
	v_exp_f32_e32 v157, v157
	v_exp_f32_e32 v158, v158
	v_exp_f32_e32 v159, v159
	v_exp_f32_e32 v160, v160
	v_exp_f32_e32 v161, v161
	v_exp_f32_e32 v162, v162
	v_exp_f32_e32 v163, v163
	v_exp_f32_e32 v164, v164
	v_cndmask_b32_e32 v63, v237, v63, vcc
	s_cbranch_execz .LBB0_424
	s_branch .LBB0_425

; template <int MODE>
; DI void attn64_wave(const Params& p, int layer, int b, int hq, int qrow0, int t0, const float* rpb_lds, unsigned char* wlds) {
;     ...
;   auto tile_u = [&](int t) -> int {
;     if (t < 8) return 32 * t;
;     if (MODE == 0) return CTX + (rs + ((t - 8) >> 1)) * 64 + ((t - 8) & 1) * 32;
;     const int kt0 = t0 - 128 + 32 * (t - 8);
;     return CTX + min(max(kt0, 0), SEQ - 32);
;   };
;   auto load_tile = [&](Frag64& f, int t) { frag64_load(f, p.P, vt, b, tile_u(t), kcol, lane); };
;   unsigned char* Kw = wlds; unsigned char* Vw = wlds + W64_KB;
;   auto compute_tile = [&](const Frag64& f, int t) {
; #pragma unroll
;     for (int i = 0; i < 4; ++i) {
;       *(u32x4*)(Kw + ((lane >> 3) + 8 * i) * LDS_STRIDE + (lane & 7) * 16) = f.k[i];
;       *(u32x4*)(Vw + ((lane >> 2) + 16 * i) * W64_VSTR + (lane & 3) * 16) = f.v[i];
;     }
;     bf16x8 kf[4], vf[2][2];
; #pragma unroll
;     for (int ks = 0; ks < 4; ++ks) kf[ks] = __builtin_bit_cast(bf16x8, *(const u32x4*)(Kw + pr * LDS_STRIDE + (16 * ks + 8 * hh) * 2));
; #pragma unroll
;     for (int dh = 0; dh < 2; ++dh)
; #pragma unroll
;       for (int s2 = 0; s2 < 2; ++s2) vf[dh][s2] = __builtin_bit_cast(bf16x8, *(const u32x4*)(Vw + (32 * dh + qi) * W64_VSTR + (16 * s2 + 8 * hh) * 2));
;     f32x16 s;
; #pragma unroll
;     for (int i = 0; i < 16; ++i) s[i] = negM2;
; #pragma unroll
;     for (int ks = 0; ks < 4; ++ks) s = MFMA32(kf[ks], qf[ks], s);
;     float pe[16];
;     if (t < 8) {
; #pragma unroll
;       for (int i = 0; i < 16; ++i) pe[i] = fexp2(s[i]);
;     } else if (MODE == 0) {
;       const int kr = rs + ((t - 8) >> 1), hf = (t - 8) & 1;
;       const float* rrow = rpb + (kr - r + 7) * 31 + 15 - c;
; #pragma unroll
;       for (int i = 0; i < 16; ++i) {
;         const int kc = hf * 32 + 16 * (i >> 3) + 8 * hh + (i & 7);
;         const bool valid = (kc >= ws) && (kc < ws + 16);
;         const int kcc = min(max(kc, ws), ws + 15);
;         pe[i] = fexp2(valid ? s[i] + rrow[kcc] : -1e30f);
;       }
;     } else {
;       const int jt = t - 8, kt0 = t0 - 128 + 32 * jt;
;       const bool tile_ok = (jt < 9) && (kt0 >= 0) && (kt0 < SEQ);
; #pragma unroll
;       for (int i = 0; i < 16; ++i) {
;         const int dd = kt0 + 16 * (i >> 3) + 8 * hh + (i & 7) - qt;
;         pe[i] = fexp2((tile_ok && dd <= 128 && dd >= -128) ? s[i] : -1e30f);
;       }
;     }
;     sum16_nopk(ls, pe);
.LBB0_425:
	s_add_i32 s30, s29, 2
	s_cmp_gt_u32 s29, 15
	s_cselect_b64 s[2:3], -1, 0
	s_cmp_lt_u32 s29, 16
	s_cselect_b32 s31, s30, 0
	s_cmp_lt_u32 s31, 8
	v_cvt_pk_bf16_f32 v48, v146, v147
	v_cvt_pk_bf16_f32 v49, v148, v149
	v_cvt_pk_bf16_f32 v50, v150, v151
	v_cvt_pk_bf16_f32 v51, v156, v157
	s_cselect_b64 vcc, -1, 0
	s_lshl_b32 s31, s31, 5
	s_waitcnt lgkmcnt(3)
	v_mfma_f32_32x32x16_bf16 v[16:31], v[124:127], v[48:51], v[16:31]
	v_exp_f32_e32 v55, v63
	s_nop 0
	v_add_f32 v135, v146, v135
	v_add_f32 v135, v147, v135
	v_add_f32 v135, v148, v135
	v_add_f32 v135, v149, v135
	v_add_f32 v135, v150, v135
	v_add_f32 v135, v151, v135
	v_add_f32 v135, v156, v135
	v_add_f32 v135, v157, v135
	v_add_f32 v135, v158, v135
	v_add_f32 v135, v159, v135
	v_add_f32 v135, v160, v135
	v_add_f32 v135, v161, v135
	v_add_f32 v135, v162, v135
	v_add_f32 v135, v163, v135
	v_add_f32 v135, v164, v135
	v_add_f32 v135, v55, v135
	v_mov_b32_e32 v127, s28
	v_mov_b32_e32 v146, s22
	v_cvt_pk_bf16_f32 v52, v158, v159
	v_cvt_pk_bf16_f32 v53, v160, v161
	v_cvt_pk_bf16_f32 v54, v162, v163
	s_waitcnt lgkmcnt(1)
	v_mfma_f32_32x32x16_bf16 v[0:15], v[88:91], v[48:51], v[0:15]
	v_add_u32_e32 v48, s31, v136
	v_med3_i32 v48, v48, 0, v236
	v_add_u32_e32 v48, 0x100, v48
	v_mov_b32_e32 v49, s31
	v_cndmask_b32_e32 v192, v48, v49, vcc
	v_add_u32_e32 v126, v192, v134
	s_movk_i32 s31, 0x100
	v_cmp_gt_u32_e32 vcc, s31, v126
	s_movk_i32 s31, 0xf8
	v_cvt_pk_bf16_f32 v55, v164, v55
	v_cndmask_b32_e32 v48, v127, v146, vcc
	v_add_u32_e32 v48, v48, v126
	v_mad_i64_i32 v[48:49], s[42:43], v48, s20, v[130:131]
	v_cmp_gt_u32_e32 vcc, s31, v126
	v_mfma_f32_32x32x16_bf16 v[16:31], v[84:87], v[52:55], v[16:31]
	global_load_dwordx4 v[84:87], v[48:49], off
	v_cndmask_b32_e32 v48, v127, v146, vcc
	v_add3_u32 v48, v126, v48, 8
	v_lshl_add_u64 v[124:125], v[192:193], 1, v[128:129]
	v_mad_i64_i32 v[48:49], s[42:43], v48, s20, v[130:131]
	global_load_dwordx4 v[88:91], v[48:49], off
	s_waitcnt lgkmcnt(0)
	v_mfma_f32_32x32x16_bf16 v[0:15], v[80:83], v[52:55], v[0:15]
	global_load_dwordx4 v[80:83], v[124:125], off
	s_waitcnt vmcnt(9)
	ds_write_b128 v138, v[112:115] offset:8192
	ds_write_b128 v139, v[116:119] offset:12800
	s_waitcnt vmcnt(8)
	ds_write_b128 v138, v[120:123] offset:9344
	s_waitcnt vmcnt(7)
	ds_write_b128 v139, v[92:95] offset:14080
	s_waitcnt vmcnt(6)
	ds_write_b128 v138, v[96:99] offset:10496
	s_waitcnt vmcnt(5)
	ds_write_b128 v139, v[100:103] offset:15360
	s_waitcnt vmcnt(4)
	ds_write_b128 v138, v[104:107] offset:11648
	s_waitcnt vmcnt(3)
	ds_write_b128 v139, v[108:111] offset:16640
	ds_read_b128 v[100:103], v140 offset:8192
	ds_read_b128 v[104:107], v140 offset:8224
	v_add_co_u32_e32 v48, vcc, s61, v124
	s_movk_i32 s31, 0xf0
	s_nop 0
	v_addc_co_u32_e32 v49, vcc, 0, v125, vcc
	v_cmp_gt_u32_e32 vcc, s31, v126
	global_load_dwordx4 v[92:95], v[48:49], off
	s_movk_i32 s31, 0xe8
	v_cndmask_b32_e32 v48, v127, v146, vcc
	v_add3_u32 v48, v126, v48, 16
	v_mad_i64_i32 v[48:49], s[42:43], v48, s20, v[130:131]
	global_load_dwordx4 v[96:99], v[48:49], off
	s_waitcnt lgkmcnt(1)
	v_mfma_f32_32x32x16_bf16 v[48:63], v[100:103], v[72:75], v[32:47]
	v_add_co_u32_e32 v100, vcc, s62, v124
	s_nop 1
	v_addc_co_u32_e32 v101, vcc, 0, v125, vcc
	v_cmp_gt_u32_e32 vcc, s31, v126
	global_load_dwordx4 v[100:103], v[100:101], off
	s_waitcnt lgkmcnt(0)
	v_mfma_f32_32x32x16_bf16 v[48:63], v[104:107], v[64:67], v[48:63]
	v_cndmask_b32_e32 v108, v127, v146, vcc
	v_add3_u32 v112, v126, v108, 24
	ds_read_b128 v[108:111], v140 offset:8256
	ds_read_b128 v[146:149], v140 offset:8288
	v_mad_i64_i32 v[104:105], s[42:43], v112, s20, v[130:131]
	v_add_co_u32_e32 v112, vcc, s64, v124
	global_load_dwordx4 v[104:107], v[104:105], off
	s_nop 0
	v_addc_co_u32_e32 v113, vcc, 0, v125, vcc
	s_waitcnt lgkmcnt(1)
	v_mfma_f32_32x32x16_bf16 v[48:63], v[108:111], v[68:71], v[48:63]
	global_load_dwordx4 v[108:111], v[112:113], off
	ds_read_b128 v[120:123], v141 offset:12800
	ds_read_b128 v[112:115], v141 offset:12832
	ds_read_b128 v[124:127], v141 offset:15360
	ds_read_b128 v[116:119], v141 offset:15392
	s_sub_u32 s100, s29, 8
	s_cmp_lt_u32 s100, 7
	s_cselect_b64 s[100:101], s[98:99], 0
	s_andn2_b64 s[100:101], s[24:25], s[100:101]
	s_and_b64 vcc, exec, s[100:101]
	s_waitcnt lgkmcnt(4)
	v_mfma_f32_32x32x16_bf16 v[48:63], v[146:149], v[76:79], v[48:63]
	s_cbranch_vccz .LBB0_427
; DI float fexp2(float x) { return __builtin_amdgcn_exp2f(x); }
; template <int MODE>
; DI void attn64_wave(const Params& p, int layer, int b, int hq, int qrow0, int t0, const float* rpb_lds, unsigned char* wlds) {
;     ...
;       const int jt = t - 8, kt0 = t0 - 128 + 32 * jt;
;       const bool tile_ok = (jt < 9) && (kt0 >= 0) && (kt0 < SEQ);
; #pragma unroll
;       for (int i = 0; i < 16; ++i) {
;         const int dd = kt0 + 16 * (i >> 3) + 8 * hh + (i & 7) - qt;
;         pe[i] = fexp2((tile_ok && dd <= 128 && dd >= -128) ? s[i] : -1e30f);
;       }
	s_add_i32 s24, s29, 1
	s_cmp_lt_u32 s24, 17
	s_movk_i32 s29, 0x4000
	s_cselect_b64 s[24:25], -1, 0
	v_cmp_gt_u32_e32 vcc, s29, v142
	v_add_u32_e32 v142, 0xffffff00, v143
	s_movk_i32 s29, 0x101
	s_and_b64 s[24:25], s[24:25], vcc
	v_cmp_gt_u32_e32 vcc, s29, v142
	s_and_b64 vcc, s[24:25], vcc
	v_add_u32_e32 v146, 0xffffff01, v143
	v_cndmask_b32_e32 v142, v237, v48, vcc
	v_cmp_gt_u32_e32 vcc, s29, v146
	s_and_b64 vcc, s[24:25], vcc
	v_add_u32_e32 v147, 0xffffff02, v143
	v_cndmask_b32_e32 v146, v237, v49, vcc
	v_cmp_gt_u32_e32 vcc, s29, v147
	s_and_b64 vcc, s[24:25], vcc
	v_add_u32_e32 v148, 0xffffff03, v143
	v_cndmask_b32_e32 v147, v237, v50, vcc
	v_cmp_gt_u32_e32 vcc, s29, v148
	s_and_b64 vcc, s[24:25], vcc
	v_add_u32_e32 v149, 0xffffff04, v143
	v_cndmask_b32_e32 v148, v237, v51, vcc
	v_cmp_gt_u32_e32 vcc, s29, v149
	s_and_b64 vcc, s[24:25], vcc
	v_add_u32_e32 v150, 0xffffff05, v143
	v_cndmask_b32_e32 v149, v237, v52, vcc
	v_cmp_gt_u32_e32 vcc, s29, v150
	s_and_b64 vcc, s[24:25], vcc
	v_add_u32_e32 v151, 0xffffff06, v143
	v_cndmask_b32_e32 v150, v237, v53, vcc
	v_cmp_gt_u32_e32 vcc, s29, v151
	s_and_b64 vcc, s[24:25], vcc
	v_add_u32_e32 v156, 0xffffff07, v143
	v_cndmask_b32_e32 v151, v237, v54, vcc
	v_cmp_gt_u32_e32 vcc, s29, v156
	s_and_b64 vcc, s[24:25], vcc
	v_add_u32_e32 v158, 0xffffff11, v143
	v_cndmask_b32_e32 v156, v237, v55, vcc
	v_exp_f32_e32 v157, v156
	v_add_u32_e32 v156, 0xffffff10, v143
	v_cmp_gt_u32_e32 vcc, s29, v156
	s_and_b64 vcc, s[24:25], vcc
	v_add_u32_e32 v159, 0xffffff12, v143
	v_cndmask_b32_e32 v156, v237, v56, vcc
	v_cmp_gt_u32_e32 vcc, s29, v158
	s_and_b64 vcc, s[24:25], vcc
	v_add_u32_e32 v160, 0xffffff13, v143
	v_cndmask_b32_e32 v158, v237, v57, vcc
	v_cmp_gt_u32_e32 vcc, s29, v159
	s_and_b64 vcc, s[24:25], vcc
	v_add_u32_e32 v161, 0xffffff14, v143
	v_cndmask_b32_e32 v159, v237, v58, vcc
	v_cmp_gt_u32_e32 vcc, s29, v160
	s_and_b64 vcc, s[24:25], vcc
	v_add_u32_e32 v162, 0xffffff15, v143
	v_cndmask_b32_e32 v160, v237, v59, vcc
	v_cmp_gt_u32_e32 vcc, s29, v161
	s_and_b64 vcc, s[24:25], vcc
	v_add_u32_e32 v163, 0xffffff16, v143
	v_cndmask_b32_e32 v161, v237, v60, vcc
	v_cmp_gt_u32_e32 vcc, s29, v162
	s_and_b64 vcc, s[24:25], vcc
	v_add_u32_e32 v143, 0xffffff17, v143
	v_cndmask_b32_e32 v162, v237, v61, vcc
	v_cmp_gt_u32_e32 vcc, s29, v163
	s_and_b64 vcc, s[24:25], vcc
	v_exp_f32_e32 v142, v142
	v_cndmask_b32_e32 v163, v237, v62, vcc
	v_cmp_gt_u32_e32 vcc, s29, v143
	s_and_b64 vcc, s[24:25], vcc
	v_exp_f32_e32 v146, v146
	v_exp_f32_e32 v147, v147
	v_exp_f32_e32 v148, v148
	v_exp_f32_e32 v149, v149
	v_exp_f32_e32 v150, v150
	v_exp_f32_e32 v151, v151
	v_exp_f32_e32 v156, v156
	v_exp_f32_e32 v158, v158
	v_exp_f32_e32 v159, v159
	v_exp_f32_e32 v160, v160
	v_exp_f32_e32 v161, v161
	v_exp_f32_e32 v162, v162
	v_exp_f32_e32 v163, v163
	v_cndmask_b32_e32 v63, v237, v63, vcc
	s_cbranch_execnz .LBB0_420
	s_branch .LBB0_428
